# hand-scheduled MLA tile body (no pk_add/mov junk, early LDS prefetch) + phase-0 weight-conversion wave rotation
# speedup vs baseline: 1.2664x; 1.2664x over previous
.LBB0_29:
	s_addk_i32 s15, 0xff80
.Lrot0_1:
	s_cmp_lt_i32 s15, 0
	s_cselect_b32 s6, s12, 0
	s_add_i32 s15, s15, s6
	s_cmp_lt_i32 s15, 0
	s_cbranch_scc1 .Lrot0_1
	s_lshl_b32 s10, s15, 5
	s_cmpk_gt_i32 s15, 0x7f
	s_cselect_b64 s[0:1], -1, 0
	s_add_i32 s4, s4, 1
	s_cmp_eq_u32 s4, 4
	s_cbranch_scc1 .LBB0_33

.LBB0_36:
	s_addk_i32 s15, 0xfe00
.Lrot0_2:
	s_cmp_lt_i32 s15, 0
	s_cselect_b32 s6, s12, 0
	s_add_i32 s15, s15, s6
	s_cmp_lt_i32 s15, 0
	s_cbranch_scc1 .Lrot0_2
	s_cmpk_lt_i32 s15, 0x200
	s_cselect_b64 s[4:5], -1, 0
	s_add_i32 s6, 0, 0x20898
	v_mov_b32_e32 v4, s6
	ds_read_b64 v[4:5], v4
	s_andn2_b64 vcc, exec, s[4:5]
	s_waitcnt lgkmcnt(0)
	v_readfirstlane_b32 s5, v5
	v_readfirstlane_b32 s4, v4
	s_cbranch_vccnz .LBB0_39
	s_nop 0
	v_lshl_add_u64 v[4:5], v[40:41], 2, s[4:5]
	s_mov_b64 s[4:5], 0x2600000
	v_lshl_add_u64 v[6:7], v[2:3], 0, s[4:5]
	s_lshl_b32 s8, s15, 5
	v_add_u32_e32 v8, 0x1080, v56
	v_add_u32_e32 v9, 0x1088, v56
	v_add_u32_e32 v10, 0x14a0, v56
	v_add_u32_e32 v11, 0x14a8, v56
	v_add_u32_e32 v12, 0x18c0, v56
	v_add_u32_e32 v13, 0x18c8, v56
	v_add_u32_e32 v14, 0x1ce0, v56
	v_add_u32_e32 v15, 0x1ce8, v56
	s_mov_b32 s9, s15

.Lrot0_3:
	s_cmp_lt_i32 s15, 0
	s_cselect_b32 s4, s12, 0
	s_add_i32 s15, s15, s4
	s_cmp_lt_i32 s15, 0
	s_cbranch_scc1 .Lrot0_3
	s_cmpk_gt_i32 s15, 0x7f
	s_cselect_b64 s[0:1], -1, 0
	s_add_i32 s4, 0, 0x20890
	v_mov_b32_e32 v4, s4
	ds_read_b64 v[4:5], v4
	s_and_b64 vcc, exec, s[0:1]
	s_waitcnt lgkmcnt(0)
	v_readfirstlane_b32 s1, v5
	v_readfirstlane_b32 s0, v4
	s_cbranch_vccnz .LBB0_42
	s_nop 0
	v_lshl_add_u64 v[4:5], v[40:41], 2, s[0:1]
	s_mov_b64 s[0:1], 0x2800000
	v_lshl_add_u64 v[6:7], v[2:3], 0, s[0:1]
	s_lshl_b32 s6, s15, 5
	v_add_u32_e32 v8, 0x1080, v56
	v_add_u32_e32 v9, 0x1088, v56
	v_add_u32_e32 v10, 0x14a0, v56
	v_add_u32_e32 v11, 0x14a8, v56
	v_add_u32_e32 v12, 0x18c0, v56
	v_add_u32_e32 v13, 0x18c8, v56
	v_add_u32_e32 v14, 0x1ce0, v56
	v_add_u32_e32 v15, 0x1ce8, v56
	s_mov_b32 s7, s15

.Lrot0_4:
	s_cmp_lt_i32 s15, 0
	s_cselect_b32 s0, s12, 0
	s_add_i32 s15, s15, s0
	s_cmp_lt_i32 s15, 0
	s_cbranch_scc1 .Lrot0_4
	s_add_i32 s0, 0, 0x20838
	v_mov_b32_e32 v4, s0
	s_add_i32 s0, 0, 0x20830
	v_mov_b32_e32 v6, s0
	ds_read_b64 v[4:5], v4
	ds_read_b64 v[6:7], v6
	s_cmp_gt_i32 s15, 47
	v_ashrrev_i32_e32 v39, 31, v38
	v_or_b32_e32 v61, 32, v38
	s_waitcnt lgkmcnt(0)
	v_readfirstlane_b32 s1, v5
	v_readfirstlane_b32 s0, v4
	v_readfirstlane_b32 s5, v7
	v_readfirstlane_b32 s4, v6
	v_or_b32_e32 v62, 40, v38
	v_or_b32_e32 v63, 48, v38
	v_or_b32_e32 v64, 56, v38
	s_cbranch_scc1 .LBB0_61
	s_cmp_lg_u64 s[4:5], 0
	v_lshl_add_u64 v[44:45], v[40:41], 2, s[0:1]
	s_cselect_b64 s[0:1], -1, 0
	s_mov_b64 s[6:7], 0x2880000
	v_mul_i32_i24_e32 v4, 0x84, v61
	v_mul_i32_i24_e32 v5, 0x84, v62
	v_mul_i32_i24_e32 v6, 0x84, v63
	v_mul_i32_i24_e32 v7, 0x84, v64
	v_lshl_add_u64 v[46:47], v[2:3], 0, s[6:7]
	v_cndmask_b32_e64 v2, 0, 1, s[0:1]
	s_lshl_b32 s17, s15, 5
	s_movk_i32 s18, 0x600
	v_cmp_ne_u32_e64 s[0:1], 1, v2
	v_add_u32_e32 v65, v60, v5
	v_add_u32_e32 v66, v60, v7
	v_add_u32_e32 v67, v60, v4
	v_add_u32_e32 v68, v60, v6
	s_mov_b32 s19, s15
	s_branch .LBB0_45

.LBB0_61:
	s_addk_i32 s15, 0xffd0
.Lrot0_5:
	s_cmp_lt_i32 s15, 0
	s_cselect_b32 s0, s12, 0
	s_add_i32 s15, s15, s0
	s_cmp_lt_i32 s15, 0
	s_cbranch_scc1 .Lrot0_5
	s_add_u32 s6, s2, 0x28c0000
	s_addc_u32 s7, s3, 0
	s_add_i32 s0, 0, 0x20848
	v_mov_b32_e32 v2, s0
	s_add_i32 s0, 0, 0x20840
	v_mov_b32_e32 v4, s0
	ds_read_b64 v[2:3], v2
	ds_read_b64 v[4:5], v4
	s_cmp_gt_i32 s15, 31
	s_waitcnt lgkmcnt(0)
	v_readfirstlane_b32 s1, v3
	v_readfirstlane_b32 s0, v2
	v_readfirstlane_b32 s5, v5
	v_readfirstlane_b32 s4, v4
	s_cbranch_scc1 .LBB0_80
	s_cmp_lg_u64 s[4:5], 0
	v_lshl_add_u64 v[40:41], v[40:41], 2, s[0:1]
	s_cselect_b64 s[0:1], -1, 0
	v_mul_i32_i24_e32 v2, 0x84, v61
	v_mul_i32_i24_e32 v3, 0x84, v62
	v_mul_i32_i24_e32 v4, 0x84, v63
	v_mul_i32_i24_e32 v5, 0x84, v64
	v_cndmask_b32_e64 v6, 0, 1, s[0:1]
	v_lshl_add_u64 v[42:43], v[42:43], 1, s[6:7]
	s_lshl_b32 s17, s15, 5
	v_cmp_ne_u32_e64 s[0:1], 1, v6
	v_add_u32_e32 v44, v60, v3
	v_add_u32_e32 v45, v60, v5
	v_add_u32_e32 v46, v60, v2
	v_add_u32_e32 v47, v60, v4
	s_mov_b32 s18, s15
	s_branch .LBB0_64

.LBB0_481:
	s_and_b32 s12, s29, 1
	s_mul_i32 s13, s12, 0x6000
	v_add_u32_e32 v242, s13, v237
	v_mov_b32_e32 v244, v152
	v_mov_b32_e32 v245, v153
	ds_read_b128 v[144:147], v242
	ds_read_b128 v[148:151], v242 offset:1024
	ds_read_b128 v[152:155], v242 offset:2048
	ds_read_b128 v[156:159], v242 offset:3072
	ds_read_b128 v[160:163], v242 offset:4096
	ds_read_b128 v[164:167], v242 offset:5120
	v_lshl_add_u32 v241, s12, 14, v238
	v_add_u32_e32 v232, v241, v240
	v_add_u32_e32 v241, v241, v239
	s_waitcnt lgkmcnt(5)
	v_mfma_f32_32x32x16_bf16 v[80:95], v[144:147], v[184:187], v[64:79]
	v_mfma_f32_32x32x16_bf16 v[96:111], v[144:147], v[200:203], v[64:79]
	ds_read_b128 v[144:147], v242 offset:6144
	s_waitcnt lgkmcnt(5)
	v_mfma_f32_32x32x16_bf16 v[80:95], v[148:151], v[188:191], v[80:95]
	v_mfma_f32_32x32x16_bf16 v[96:111], v[148:151], v[204:207], v[96:111]
	ds_read_b128 v[148:151], v242 offset:7168
	s_waitcnt lgkmcnt(5)
	v_mfma_f32_32x32x16_bf16 v[80:95], v[152:155], v[192:195], v[80:95]
	v_mfma_f32_32x32x16_bf16 v[96:111], v[152:155], v[208:211], v[96:111]
	ds_read_b128 v[152:155], v242 offset:8192
	s_waitcnt lgkmcnt(5)
	v_mfma_f32_32x32x16_bf16 v[80:95], v[156:159], v[196:199], v[80:95]
	v_mfma_f32_32x32x16_bf16 v[96:111], v[156:159], v[212:215], v[96:111]
	ds_read_b128 v[156:159], v242 offset:9216
	s_waitcnt lgkmcnt(5)
	v_mfma_f32_32x32x16_bf16 v[80:95], v[160:163], v[216:219], v[80:95]
	v_mfma_f32_32x32x16_bf16 v[96:111], v[160:163], v[224:227], v[96:111]
	ds_read_b128 v[160:163], v242 offset:10240
	s_waitcnt lgkmcnt(5)
	v_mfma_f32_32x32x16_bf16 v[80:95], v[164:167], v[220:223], v[80:95]
	v_mfma_f32_32x32x16_bf16 v[96:111], v[164:167], v[228:231], v[96:111]
	ds_read_b128 v[164:167], v242 offset:11264
	ds_read_b64_tr_b16 v[168:169], v241 offset:49152
	ds_read_b64_tr_b16 v[170:171], v241 offset:50176
	ds_read_b64_tr_b16 v[172:173], v241 offset:51200
	ds_read_b64_tr_b16 v[174:175], v241 offset:52224
	ds_read_b64_tr_b16 v[176:177], v232 offset:49152
	ds_read_b64_tr_b16 v[178:179], v232 offset:50176
	ds_read_b64_tr_b16 v[180:181], v232 offset:51200
	ds_read_b64_tr_b16 v[182:183], v232 offset:52224
	s_waitcnt lgkmcnt(13)
	v_mfma_f32_32x32x16_bf16 v[112:127], v[144:147], v[184:187], v[64:79]
	v_exp_f32_e32 v80, v80
	v_exp_f32_e32 v81, v81
	v_add_f32_e32 v244, v244, v80
	v_add_f32_e32 v244, v244, v81
	v_cvt_pk_bf16_f32 v80, v80, v81
	v_mfma_f32_32x32x16_bf16 v[128:143], v[144:147], v[200:203], v[64:79]
	ds_read_b128 v[144:147], v242 offset:12288
	v_exp_f32_e32 v82, v82
	v_exp_f32_e32 v83, v83
	v_add_f32_e32 v244, v244, v82
	v_add_f32_e32 v244, v244, v83
	v_cvt_pk_bf16_f32 v81, v82, v83
	s_waitcnt lgkmcnt(13)
	v_mfma_f32_32x32x16_bf16 v[112:127], v[148:151], v[188:191], v[112:127]
	v_exp_f32_e32 v84, v84
	v_exp_f32_e32 v85, v85
	v_add_f32_e32 v244, v244, v84
	v_add_f32_e32 v244, v244, v85
	v_cvt_pk_bf16_f32 v82, v84, v85
	v_mfma_f32_32x32x16_bf16 v[128:143], v[148:151], v[204:207], v[128:143]
	ds_read_b128 v[148:151], v242 offset:13312
	v_exp_f32_e32 v86, v86
	v_exp_f32_e32 v87, v87
	v_add_f32_e32 v244, v244, v86
	v_add_f32_e32 v244, v244, v87
	s_waitcnt lgkmcnt(13)
	v_mfma_f32_32x32x16_bf16 v[112:127], v[152:155], v[192:195], v[112:127]
	v_cvt_pk_bf16_f32 v83, v86, v87
	v_exp_f32_e32 v96, v96
	v_exp_f32_e32 v97, v97
	v_add_f32_e32 v245, v245, v96
	v_mfma_f32_32x32x16_bf16 v[128:143], v[152:155], v[208:211], v[128:143]
	ds_read_b128 v[152:155], v242 offset:14336
	v_add_f32_e32 v245, v245, v97
	v_cvt_pk_bf16_f32 v96, v96, v97
	v_exp_f32_e32 v98, v98
	v_exp_f32_e32 v99, v99
	s_waitcnt lgkmcnt(9)
	v_mfma_f32_32x32x16_bf16 v[48:63], v[80:83], v[168:171], v[48:63]
	v_add_f32_e32 v245, v245, v98
	v_add_f32_e32 v245, v245, v99
	v_cvt_pk_bf16_f32 v97, v98, v99
	v_exp_f32_e32 v100, v100
	v_exp_f32_e32 v101, v101
	v_mfma_f32_32x32x16_bf16 v[112:127], v[156:159], v[196:199], v[112:127]
	v_add_f32_e32 v245, v245, v100
	v_add_f32_e32 v245, v245, v101
	v_cvt_pk_bf16_f32 v98, v100, v101
	v_exp_f32_e32 v102, v102
	v_exp_f32_e32 v103, v103
	s_waitcnt lgkmcnt(5)
	v_mfma_f32_32x32x16_bf16 v[32:47], v[80:83], v[176:179], v[32:47]
	v_add_f32_e32 v245, v245, v102
	v_add_f32_e32 v245, v245, v103
	v_cvt_pk_bf16_f32 v99, v102, v103
	v_exp_f32_e32 v88, v88
	v_mfma_f32_32x32x16_bf16 v[128:143], v[156:159], v[212:215], v[128:143]
	ds_read_b128 v[156:159], v242 offset:15360
	v_exp_f32_e32 v89, v89
	v_add_f32_e32 v244, v244, v88
	v_add_f32_e32 v244, v244, v89
	v_cvt_pk_bf16_f32 v88, v88, v89
	v_mfma_f32_32x32x16_bf16 v[112:127], v[160:163], v[216:219], v[112:127]
	v_exp_f32_e32 v90, v90
	v_exp_f32_e32 v91, v91
	v_add_f32_e32 v244, v244, v90
	v_add_f32_e32 v244, v244, v91
	v_cvt_pk_bf16_f32 v89, v90, v91
	v_mfma_f32_32x32x16_bf16 v[128:143], v[160:163], v[224:227], v[128:143]
	ds_read_b128 v[160:163], v242 offset:16384
	v_exp_f32_e32 v92, v92
	v_exp_f32_e32 v93, v93
	v_add_f32_e32 v244, v244, v92
	v_add_f32_e32 v244, v244, v93
	v_cvt_pk_bf16_f32 v90, v92, v93
	v_mfma_f32_32x32x16_bf16 v[16:31], v[96:99], v[168:171], v[16:31]
	v_exp_f32_e32 v94, v94
	v_exp_f32_e32 v95, v95
	v_add_f32_e32 v244, v244, v94
	v_add_f32_e32 v244, v244, v95
	v_mfma_f32_32x32x16_bf16 v[112:127], v[164:167], v[220:223], v[112:127]
	v_cvt_pk_bf16_f32 v91, v94, v95
	v_exp_f32_e32 v104, v104
	v_exp_f32_e32 v105, v105
	v_add_f32_e32 v245, v245, v104
	v_mfma_f32_32x32x16_bf16 v[0:15], v[96:99], v[176:179], v[0:15]
	v_add_f32_e32 v245, v245, v105
	v_cvt_pk_bf16_f32 v104, v104, v105
	v_exp_f32_e32 v106, v106
	v_exp_f32_e32 v107, v107
	v_add_f32_e32 v245, v245, v106
	v_mfma_f32_32x32x16_bf16 v[128:143], v[164:167], v[228:231], v[128:143]
	ds_read_b128 v[164:167], v242 offset:17408
	v_add_f32_e32 v245, v245, v107
	v_cvt_pk_bf16_f32 v105, v106, v107
	v_exp_f32_e32 v108, v108
	v_exp_f32_e32 v109, v109
	v_add_f32_e32 v245, v245, v108
	v_mfma_f32_32x32x16_bf16 v[48:63], v[88:91], v[172:175], v[48:63]
	v_add_f32_e32 v245, v245, v109
	v_cvt_pk_bf16_f32 v106, v108, v109
	v_exp_f32_e32 v110, v110
	v_exp_f32_e32 v111, v111
	s_waitcnt lgkmcnt(6)
	v_mfma_f32_32x32x16_bf16 v[32:47], v[88:91], v[180:183], v[32:47]
	v_add_f32_e32 v245, v245, v110
	v_add_f32_e32 v245, v245, v111
	v_cvt_pk_bf16_f32 v107, v110, v111
	ds_read_b64_tr_b16 v[168:169], v241 offset:53248
	ds_read_b64_tr_b16 v[170:171], v241 offset:54272
	ds_read_b64_tr_b16 v[176:177], v232 offset:53248
	ds_read_b64_tr_b16 v[178:179], v232 offset:54272
	v_mfma_f32_32x32x16_bf16 v[16:31], v[104:107], v[172:175], v[16:31]
	ds_read_b64_tr_b16 v[172:173], v241 offset:55296
	ds_read_b64_tr_b16 v[174:175], v241 offset:56320
	v_mfma_f32_32x32x16_bf16 v[0:15], v[104:107], v[180:183], v[0:15]
	ds_read_b64_tr_b16 v[180:181], v232 offset:55296
	ds_read_b64_tr_b16 v[182:183], v232 offset:56320
	s_waitcnt lgkmcnt(13)
	v_mfma_f32_32x32x16_bf16 v[80:95], v[144:147], v[184:187], v[64:79]
	v_exp_f32_e32 v112, v112
	v_exp_f32_e32 v113, v113
	v_add_f32_e32 v244, v244, v112
	v_add_f32_e32 v244, v244, v113
	v_cvt_pk_bf16_f32 v112, v112, v113
	v_mfma_f32_32x32x16_bf16 v[96:111], v[144:147], v[200:203], v[64:79]
	ds_read_b128 v[144:147], v242 offset:18432
	v_exp_f32_e32 v114, v114
	v_exp_f32_e32 v115, v115
	v_add_f32_e32 v244, v244, v114
	v_add_f32_e32 v244, v244, v115
	v_cvt_pk_bf16_f32 v113, v114, v115
	s_waitcnt lgkmcnt(13)
	v_mfma_f32_32x32x16_bf16 v[80:95], v[148:151], v[188:191], v[80:95]
	v_exp_f32_e32 v116, v116
	v_exp_f32_e32 v117, v117
	v_add_f32_e32 v244, v244, v116
	v_add_f32_e32 v244, v244, v117
	v_cvt_pk_bf16_f32 v114, v116, v117
	v_mfma_f32_32x32x16_bf16 v[96:111], v[148:151], v[204:207], v[96:111]
	ds_read_b128 v[148:151], v242 offset:19456
	v_exp_f32_e32 v118, v118
	v_exp_f32_e32 v119, v119
	v_add_f32_e32 v244, v244, v118
	v_add_f32_e32 v244, v244, v119
	s_waitcnt lgkmcnt(13)
	v_mfma_f32_32x32x16_bf16 v[80:95], v[152:155], v[192:195], v[80:95]
	v_cvt_pk_bf16_f32 v115, v118, v119
	v_exp_f32_e32 v128, v128
	v_exp_f32_e32 v129, v129
	v_add_f32_e32 v245, v245, v128
	v_mfma_f32_32x32x16_bf16 v[96:111], v[152:155], v[208:211], v[96:111]
	ds_read_b128 v[152:155], v242 offset:20480
	v_add_f32_e32 v245, v245, v129
	v_cvt_pk_bf16_f32 v128, v128, v129
	v_exp_f32_e32 v130, v130
	v_exp_f32_e32 v131, v131
	s_waitcnt lgkmcnt(9)
	v_mfma_f32_32x32x16_bf16 v[48:63], v[112:115], v[168:171], v[48:63]
	v_add_f32_e32 v245, v245, v130
	v_add_f32_e32 v245, v245, v131
	v_cvt_pk_bf16_f32 v129, v130, v131
	v_exp_f32_e32 v132, v132
	v_exp_f32_e32 v133, v133
	v_mfma_f32_32x32x16_bf16 v[80:95], v[156:159], v[196:199], v[80:95]
	v_add_f32_e32 v245, v245, v132
	v_add_f32_e32 v245, v245, v133
	v_cvt_pk_bf16_f32 v130, v132, v133
	v_exp_f32_e32 v134, v134
	v_exp_f32_e32 v135, v135
	s_waitcnt lgkmcnt(7)
	v_mfma_f32_32x32x16_bf16 v[32:47], v[112:115], v[176:179], v[32:47]
	v_add_f32_e32 v245, v245, v134
	v_add_f32_e32 v245, v245, v135
	v_cvt_pk_bf16_f32 v131, v134, v135
	v_exp_f32_e32 v120, v120
	v_mfma_f32_32x32x16_bf16 v[96:111], v[156:159], v[212:215], v[96:111]
	ds_read_b128 v[156:159], v242 offset:21504
	v_exp_f32_e32 v121, v121
	v_add_f32_e32 v244, v244, v120
	v_add_f32_e32 v244, v244, v121
	v_cvt_pk_bf16_f32 v120, v120, v121
	v_mfma_f32_32x32x16_bf16 v[80:95], v[160:163], v[216:219], v[80:95]
	v_exp_f32_e32 v122, v122
	v_exp_f32_e32 v123, v123
	v_add_f32_e32 v244, v244, v122
	v_add_f32_e32 v244, v244, v123
	v_cvt_pk_bf16_f32 v121, v122, v123
	v_mfma_f32_32x32x16_bf16 v[96:111], v[160:163], v[224:227], v[96:111]
	ds_read_b128 v[160:163], v242 offset:22528
	v_exp_f32_e32 v124, v124
	v_exp_f32_e32 v125, v125
	v_add_f32_e32 v244, v244, v124
	v_add_f32_e32 v244, v244, v125
	v_cvt_pk_bf16_f32 v122, v124, v125
	v_mfma_f32_32x32x16_bf16 v[16:31], v[128:131], v[168:171], v[16:31]
	v_exp_f32_e32 v126, v126
	v_exp_f32_e32 v127, v127
	v_add_f32_e32 v244, v244, v126
	v_add_f32_e32 v244, v244, v127
	v_mfma_f32_32x32x16_bf16 v[80:95], v[164:167], v[220:223], v[80:95]
	v_cvt_pk_bf16_f32 v123, v126, v127
	v_exp_f32_e32 v136, v136
	v_exp_f32_e32 v137, v137
	v_add_f32_e32 v245, v245, v136
	v_mfma_f32_32x32x16_bf16 v[0:15], v[128:131], v[176:179], v[0:15]
	v_add_f32_e32 v245, v245, v137
	v_cvt_pk_bf16_f32 v136, v136, v137
	v_exp_f32_e32 v138, v138
	v_exp_f32_e32 v139, v139
	v_add_f32_e32 v245, v245, v138
	v_mfma_f32_32x32x16_bf16 v[96:111], v[164:167], v[228:231], v[96:111]
	ds_read_b128 v[164:167], v242 offset:23552
	v_add_f32_e32 v245, v245, v139
	v_cvt_pk_bf16_f32 v137, v138, v139
	v_exp_f32_e32 v140, v140
	v_exp_f32_e32 v141, v141
	v_add_f32_e32 v245, v245, v140
	s_waitcnt lgkmcnt(8)
	v_mfma_f32_32x32x16_bf16 v[48:63], v[120:123], v[172:175], v[48:63]
	v_add_f32_e32 v245, v245, v141
	v_cvt_pk_bf16_f32 v138, v140, v141
	v_exp_f32_e32 v142, v142
	v_exp_f32_e32 v143, v143
	s_waitcnt lgkmcnt(6)
	v_mfma_f32_32x32x16_bf16 v[32:47], v[120:123], v[180:183], v[32:47]
	v_add_f32_e32 v245, v245, v142
	v_add_f32_e32 v245, v245, v143
	v_cvt_pk_bf16_f32 v139, v142, v143
	ds_read_b64_tr_b16 v[168:169], v241 offset:57344
	ds_read_b64_tr_b16 v[170:171], v241 offset:58368
	ds_read_b64_tr_b16 v[176:177], v232 offset:57344
	ds_read_b64_tr_b16 v[178:179], v232 offset:58368
	v_mfma_f32_32x32x16_bf16 v[16:31], v[136:139], v[172:175], v[16:31]
	ds_read_b64_tr_b16 v[172:173], v241 offset:59392
	ds_read_b64_tr_b16 v[174:175], v241 offset:60416
	v_mfma_f32_32x32x16_bf16 v[0:15], v[136:139], v[180:183], v[0:15]
	ds_read_b64_tr_b16 v[180:181], v232 offset:59392
	ds_read_b64_tr_b16 v[182:183], v232 offset:60416
	s_waitcnt lgkmcnt(13)
	v_mfma_f32_32x32x16_bf16 v[112:127], v[144:147], v[184:187], v[64:79]
	v_exp_f32_e32 v80, v80
	v_exp_f32_e32 v81, v81
	v_add_f32_e32 v244, v244, v80
	v_add_f32_e32 v244, v244, v81
	v_cvt_pk_bf16_f32 v80, v80, v81
	v_mfma_f32_32x32x16_bf16 v[128:143], v[144:147], v[200:203], v[64:79]
	v_exp_f32_e32 v82, v82
	v_exp_f32_e32 v83, v83
	v_add_f32_e32 v244, v244, v82
	v_add_f32_e32 v244, v244, v83
	v_cvt_pk_bf16_f32 v81, v82, v83
	s_waitcnt lgkmcnt(12)
	v_mfma_f32_32x32x16_bf16 v[112:127], v[148:151], v[188:191], v[112:127]
	v_exp_f32_e32 v84, v84
	v_exp_f32_e32 v85, v85
	v_add_f32_e32 v244, v244, v84
	v_add_f32_e32 v244, v244, v85
	v_cvt_pk_bf16_f32 v82, v84, v85
	v_mfma_f32_32x32x16_bf16 v[128:143], v[148:151], v[204:207], v[128:143]
	v_exp_f32_e32 v86, v86
	v_exp_f32_e32 v87, v87
	v_add_f32_e32 v244, v244, v86
	v_add_f32_e32 v244, v244, v87
	s_waitcnt lgkmcnt(11)
	v_mfma_f32_32x32x16_bf16 v[112:127], v[152:155], v[192:195], v[112:127]
	v_cvt_pk_bf16_f32 v83, v86, v87
	v_exp_f32_e32 v96, v96
	v_exp_f32_e32 v97, v97
	v_add_f32_e32 v245, v245, v96
	v_mfma_f32_32x32x16_bf16 v[128:143], v[152:155], v[208:211], v[128:143]
	v_add_f32_e32 v245, v245, v97
	v_cvt_pk_bf16_f32 v96, v96, v97
	v_exp_f32_e32 v98, v98
	v_exp_f32_e32 v99, v99
	s_waitcnt lgkmcnt(6)
	v_mfma_f32_32x32x16_bf16 v[48:63], v[80:83], v[168:171], v[48:63]
	v_add_f32_e32 v245, v245, v98
	v_add_f32_e32 v245, v245, v99
	v_cvt_pk_bf16_f32 v97, v98, v99
	v_exp_f32_e32 v100, v100
	v_exp_f32_e32 v101, v101
	v_mfma_f32_32x32x16_bf16 v[112:127], v[156:159], v[196:199], v[112:127]
	v_add_f32_e32 v245, v245, v100
	v_add_f32_e32 v245, v245, v101
	v_cvt_pk_bf16_f32 v98, v100, v101
	v_exp_f32_e32 v102, v102
	v_exp_f32_e32 v103, v103
	s_waitcnt lgkmcnt(4)
	v_mfma_f32_32x32x16_bf16 v[32:47], v[80:83], v[176:179], v[32:47]
	v_add_f32_e32 v245, v245, v102
	v_add_f32_e32 v245, v245, v103
	v_cvt_pk_bf16_f32 v99, v102, v103
	v_exp_f32_e32 v88, v88
	v_mfma_f32_32x32x16_bf16 v[128:143], v[156:159], v[212:215], v[128:143]
	v_exp_f32_e32 v89, v89
	v_add_f32_e32 v244, v244, v88
	v_add_f32_e32 v244, v244, v89
	v_cvt_pk_bf16_f32 v88, v88, v89
	v_mfma_f32_32x32x16_bf16 v[112:127], v[160:163], v[216:219], v[112:127]
	v_exp_f32_e32 v90, v90
	v_exp_f32_e32 v91, v91
	v_add_f32_e32 v244, v244, v90
	v_add_f32_e32 v244, v244, v91
	v_cvt_pk_bf16_f32 v89, v90, v91
	v_mfma_f32_32x32x16_bf16 v[128:143], v[160:163], v[224:227], v[128:143]
	v_exp_f32_e32 v92, v92
	v_exp_f32_e32 v93, v93
	v_add_f32_e32 v244, v244, v92
	v_add_f32_e32 v244, v244, v93
	v_cvt_pk_bf16_f32 v90, v92, v93
	v_mfma_f32_32x32x16_bf16 v[16:31], v[96:99], v[168:171], v[16:31]
	v_exp_f32_e32 v94, v94
	v_exp_f32_e32 v95, v95
	v_add_f32_e32 v244, v244, v94
	v_add_f32_e32 v244, v244, v95
	v_mfma_f32_32x32x16_bf16 v[112:127], v[164:167], v[220:223], v[112:127]
	v_cvt_pk_bf16_f32 v91, v94, v95
	v_exp_f32_e32 v104, v104
	v_exp_f32_e32 v105, v105
	v_add_f32_e32 v245, v245, v104
	v_mfma_f32_32x32x16_bf16 v[0:15], v[96:99], v[176:179], v[0:15]
	v_add_f32_e32 v245, v245, v105
	v_cvt_pk_bf16_f32 v104, v104, v105
	v_exp_f32_e32 v106, v106
	v_exp_f32_e32 v107, v107
	v_add_f32_e32 v245, v245, v106
	v_mfma_f32_32x32x16_bf16 v[128:143], v[164:167], v[228:231], v[128:143]
	v_add_f32_e32 v245, v245, v107
	v_cvt_pk_bf16_f32 v105, v106, v107
	v_exp_f32_e32 v108, v108
	v_exp_f32_e32 v109, v109
	v_add_f32_e32 v245, v245, v108
	s_waitcnt lgkmcnt(2)
	v_mfma_f32_32x32x16_bf16 v[48:63], v[88:91], v[172:175], v[48:63]
	v_add_f32_e32 v245, v245, v109
	v_cvt_pk_bf16_f32 v106, v108, v109
	v_exp_f32_e32 v110, v110
	v_exp_f32_e32 v111, v111
	s_waitcnt lgkmcnt(0)
	v_mfma_f32_32x32x16_bf16 v[32:47], v[88:91], v[180:183], v[32:47]
	v_add_f32_e32 v245, v245, v110
	v_add_f32_e32 v245, v245, v111
	v_cvt_pk_bf16_f32 v107, v110, v111
	ds_read_b64_tr_b16 v[168:169], v241 offset:61440
	ds_read_b64_tr_b16 v[170:171], v241 offset:62464
	ds_read_b64_tr_b16 v[176:177], v232 offset:61440
	ds_read_b64_tr_b16 v[178:179], v232 offset:62464
	v_mfma_f32_32x32x16_bf16 v[16:31], v[104:107], v[172:175], v[16:31]
	ds_read_b64_tr_b16 v[172:173], v241 offset:63488
	ds_read_b64_tr_b16 v[174:175], v241 offset:64512
	v_mfma_f32_32x32x16_bf16 v[0:15], v[104:107], v[180:183], v[0:15]
	ds_read_b64_tr_b16 v[180:181], v232 offset:63488
	ds_read_b64_tr_b16 v[182:183], v232 offset:64512
	v_exp_f32_e32 v112, v112
	v_exp_f32_e32 v113, v113
	v_add_f32_e32 v244, v244, v112
	v_add_f32_e32 v244, v244, v113
	v_cvt_pk_bf16_f32 v112, v112, v113
	v_exp_f32_e32 v114, v114
	v_exp_f32_e32 v115, v115
	v_add_f32_e32 v244, v244, v114
	v_add_f32_e32 v244, v244, v115
	v_cvt_pk_bf16_f32 v113, v114, v115
	v_exp_f32_e32 v116, v116
	v_exp_f32_e32 v117, v117
	v_add_f32_e32 v244, v244, v116
	v_add_f32_e32 v244, v244, v117
	v_cvt_pk_bf16_f32 v114, v116, v117
	v_exp_f32_e32 v118, v118
	v_exp_f32_e32 v119, v119
	v_add_f32_e32 v244, v244, v118
	v_add_f32_e32 v244, v244, v119
	v_cvt_pk_bf16_f32 v115, v118, v119
	v_exp_f32_e32 v128, v128
	v_exp_f32_e32 v129, v129
	s_waitcnt lgkmcnt(6)
	v_mfma_f32_32x32x16_bf16 v[48:63], v[112:115], v[168:171], v[48:63]
	v_add_f32_e32 v245, v245, v128
	v_add_f32_e32 v245, v245, v129
	v_cvt_pk_bf16_f32 v128, v128, v129
	v_exp_f32_e32 v130, v130
	v_exp_f32_e32 v131, v131
	v_add_f32_e32 v245, v245, v130
	v_add_f32_e32 v245, v245, v131
	v_cvt_pk_bf16_f32 v129, v130, v131
	v_exp_f32_e32 v132, v132
	v_exp_f32_e32 v133, v133
	s_waitcnt lgkmcnt(4)
	v_mfma_f32_32x32x16_bf16 v[32:47], v[112:115], v[176:179], v[32:47]
	v_add_f32_e32 v245, v245, v132
	v_add_f32_e32 v245, v245, v133
	v_cvt_pk_bf16_f32 v130, v132, v133
	v_exp_f32_e32 v134, v134
	v_exp_f32_e32 v135, v135
	v_add_f32_e32 v245, v245, v134
	v_add_f32_e32 v245, v245, v135
	v_cvt_pk_bf16_f32 v131, v134, v135
	v_exp_f32_e32 v120, v120
	v_exp_f32_e32 v121, v121
	v_mfma_f32_32x32x16_bf16 v[16:31], v[128:131], v[168:171], v[16:31]
	v_add_f32_e32 v244, v244, v120
	v_add_f32_e32 v244, v244, v121
	v_cvt_pk_bf16_f32 v120, v120, v121
	v_exp_f32_e32 v122, v122
	v_exp_f32_e32 v123, v123
	v_add_f32_e32 v244, v244, v122
	v_add_f32_e32 v244, v244, v123
	v_cvt_pk_bf16_f32 v121, v122, v123
	v_exp_f32_e32 v124, v124
	v_exp_f32_e32 v125, v125
	v_mfma_f32_32x32x16_bf16 v[0:15], v[128:131], v[176:179], v[0:15]
	v_add_f32_e32 v244, v244, v124
	v_add_f32_e32 v244, v244, v125
	v_cvt_pk_bf16_f32 v122, v124, v125
	v_exp_f32_e32 v126, v126
	v_exp_f32_e32 v127, v127
	v_add_f32_e32 v244, v244, v126
	v_add_f32_e32 v152, v244, v127
	v_cvt_pk_bf16_f32 v123, v126, v127
	v_exp_f32_e32 v136, v136
	v_exp_f32_e32 v137, v137
	s_waitcnt lgkmcnt(2)
	v_mfma_f32_32x32x16_bf16 v[48:63], v[120:123], v[172:175], v[48:63]
	v_add_f32_e32 v245, v245, v136
	v_add_f32_e32 v245, v245, v137
	v_cvt_pk_bf16_f32 v136, v136, v137
	v_exp_f32_e32 v138, v138
	v_exp_f32_e32 v139, v139
	v_add_f32_e32 v245, v245, v138
	v_add_f32_e32 v245, v245, v139
	v_cvt_pk_bf16_f32 v137, v138, v139
	v_exp_f32_e32 v140, v140
	s_waitcnt lgkmcnt(0)
	v_mfma_f32_32x32x16_bf16 v[32:47], v[120:123], v[180:183], v[32:47]
	v_exp_f32_e32 v141, v141
	v_add_f32_e32 v245, v245, v140
	v_add_f32_e32 v245, v245, v141
	v_cvt_pk_bf16_f32 v138, v140, v141
	v_exp_f32_e32 v142, v142
	v_exp_f32_e32 v143, v143
	v_add_f32_e32 v245, v245, v142
	v_add_f32_e32 v153, v245, v143
	v_cvt_pk_bf16_f32 v139, v142, v143
	s_nop 1
	v_mfma_f32_32x32x16_bf16 v[16:31], v[136:139], v[172:175], v[16:31]
	v_mfma_f32_32x32x16_bf16 v[0:15], v[136:139], v[180:183], v[0:15]
	s_nop 0
	v_max_f32_e32 v80, v152, v153
	s_mov_b32 s12, 0x5f800000
	v_cmp_lt_f32_e32 vcc, s12, v80
	s_cbranch_vccz .LBB0_483
	v_pk_mul_f32 v[152:153], v[152:153], s[92:93] op_sel_hi:[1,0]
	v_pk_mul_f32 v[62:63], v[62:63], s[92:93] op_sel_hi:[1,0]
	v_pk_mul_f32 v[60:61], v[60:61], s[92:93] op_sel_hi:[1,0]
	v_pk_mul_f32 v[58:59], v[58:59], s[92:93] op_sel_hi:[1,0]
	v_pk_mul_f32 v[56:57], v[56:57], s[92:93] op_sel_hi:[1,0]
	v_pk_mul_f32 v[54:55], v[54:55], s[92:93] op_sel_hi:[1,0]
	v_pk_mul_f32 v[52:53], v[52:53], s[92:93] op_sel_hi:[1,0]
	v_pk_mul_f32 v[50:51], v[50:51], s[92:93] op_sel_hi:[1,0]
	v_pk_mul_f32 v[48:49], v[48:49], s[92:93] op_sel_hi:[1,0]
	v_pk_mul_f32 v[46:47], v[46:47], s[92:93] op_sel_hi:[1,0]
	v_pk_mul_f32 v[44:45], v[44:45], s[92:93] op_sel_hi:[1,0]
	v_pk_mul_f32 v[42:43], v[42:43], s[92:93] op_sel_hi:[1,0]
	v_pk_mul_f32 v[40:41], v[40:41], s[92:93] op_sel_hi:[1,0]
	v_pk_mul_f32 v[38:39], v[38:39], s[92:93] op_sel_hi:[1,0]
	v_pk_mul_f32 v[36:37], v[36:37], s[92:93] op_sel_hi:[1,0]
	v_pk_mul_f32 v[34:35], v[34:35], s[92:93] op_sel_hi:[1,0]
	v_pk_mul_f32 v[32:33], v[32:33], s[92:93] op_sel_hi:[1,0]
	v_pk_mul_f32 v[30:31], v[30:31], s[92:93] op_sel_hi:[1,0]
	v_pk_mul_f32 v[28:29], v[28:29], s[92:93] op_sel_hi:[1,0]
	v_pk_mul_f32 v[26:27], v[26:27], s[92:93] op_sel_hi:[1,0]
	v_pk_mul_f32 v[24:25], v[24:25], s[92:93] op_sel_hi:[1,0]
	v_pk_mul_f32 v[22:23], v[22:23], s[92:93] op_sel_hi:[1,0]
	v_pk_mul_f32 v[20:21], v[20:21], s[92:93] op_sel_hi:[1,0]
	v_pk_mul_f32 v[18:19], v[18:19], s[92:93] op_sel_hi:[1,0]
	v_pk_mul_f32 v[16:17], v[16:17], s[92:93] op_sel_hi:[1,0]
	v_pk_mul_f32 v[14:15], v[14:15], s[92:93] op_sel_hi:[1,0]
	v_pk_mul_f32 v[12:13], v[12:13], s[92:93] op_sel_hi:[1,0]
	v_pk_mul_f32 v[10:11], v[10:11], s[92:93] op_sel_hi:[1,0]
	v_pk_mul_f32 v[8:9], v[8:9], s[92:93] op_sel_hi:[1,0]
	v_pk_mul_f32 v[6:7], v[6:7], s[92:93] op_sel_hi:[1,0]
	v_pk_mul_f32 v[4:5], v[4:5], s[92:93] op_sel_hi:[1,0]
	v_pk_mul_f32 v[2:3], v[2:3], s[92:93] op_sel_hi:[1,0]
	v_pk_mul_f32 v[0:1], v[0:1], s[92:93] op_sel_hi:[1,0]
	v_pk_add_f32 v[78:79], v[78:79], s[66:67] op_sel_hi:[1,0]
	v_pk_add_f32 v[76:77], v[76:77], s[66:67] op_sel_hi:[1,0]
	v_pk_add_f32 v[74:75], v[74:75], s[66:67] op_sel_hi:[1,0]
	v_pk_add_f32 v[72:73], v[72:73], s[66:67] op_sel_hi:[1,0]
	v_pk_add_f32 v[70:71], v[70:71], s[66:67] op_sel_hi:[1,0]
	v_pk_add_f32 v[68:69], v[68:69], s[66:67] op_sel_hi:[1,0]
	v_pk_add_f32 v[66:67], v[66:67], s[66:67] op_sel_hi:[1,0]
	v_pk_add_f32 v[64:65], v[64:65], s[66:67] op_sel_hi:[1,0]
